# peeled first K-loop iteration (first MFMA per accumulator takes C=0, no accumulator zeroing); RETT V^T epilogue with 16-byte stores
# speedup vs baseline: 1.0444x; 1.0123x over previous
.LBB0_810:
	s_add_i32 s6, s28, -2
	s_add_u32 s7, s2, 0x100
	s_addc_u32 s8, s3, 0
	s_add_u32 s2, s4, 0x80
	s_addc_u32 s3, s5, 0
	s_mov_b32 s4, 0
	s_add_i32 s9, s4, 2
	s_add_u32 s21, s2, 0x80
	s_addc_u32 s5, s3, 0
	s_add_i32 s29, 0, 0x10000
	s_cmp_eq_u32 s6, s4
	s_cselect_b32 s5, s23, s5
	s_cselect_b32 s4, s22, s21
	v_add_u32_e32 v0, s29, v204
	s_cselect_b32 s31, s25, s8
	s_cselect_b32 s30, s24, s7
	s_add_i32 s21, 0, 0x14000
	ds_read_b128 v[130:133], v0
	ds_read_b128 v[134:137], v0 offset:1024
	ds_read_b128 v[138:141], v0 offset:2048
	ds_read_b128 v[142:145], v0 offset:3072
	v_add_u32_e32 v0, s21, v204
	ds_read_b128 v[146:149], v0
	ds_read_b128 v[160:163], v0 offset:1024
	ds_read_b128 v[164:167], v0 offset:2048
	ds_read_b128 v[168:171], v0 offset:3072
	v_lshl_add_u64 v[176:177], s[2:3], 0, v[158:159]
	s_add_i32 m0, s27, 0xc000
	ds_read_b128 v[172:175], v205
	ds_read_b128 v[206:209], v205 offset:1024
	ds_read_b128 v[210:213], v205 offset:2048
	ds_read_b128 v[214:217], v205 offset:3072
	ds_read_b128 v[218:221], v205 offset:4096
	ds_read_b128 v[222:225], v205 offset:5120
	ds_read_b128 v[226:229], v205 offset:6144
	ds_read_b128 v[236:239], v205 offset:7168
	global_load_lds_dwordx4 v[176:177], off
	v_lshl_add_u64 v[176:177], s[2:3], 0, v[156:157]
	s_add_i32 m0, s27, 0xe000
	s_nop 0
	global_load_lds_dwordx4 v[176:177], off
	s_waitcnt vmcnt(8)
	s_waitcnt lgkmcnt(0)
	s_barrier
	s_setprio 1
	s_waitcnt lgkmcnt(0)
	v_mfma_f32_16x16x32_bf16 v[126:129], v[130:133], v[172:175], 0
	v_mfma_f32_16x16x32_bf16 v[118:121], v[138:141], v[172:175], 0
	v_mfma_f32_16x16x32_bf16 v[110:113], v[130:133], v[210:213], 0
	v_mfma_f32_16x16x32_bf16 v[102:105], v[138:141], v[210:213], 0
	v_mfma_f32_16x16x32_bf16 v[94:97], v[130:133], v[218:221], 0
	v_mfma_f32_16x16x32_bf16 v[86:89], v[138:141], v[218:221], 0
	v_mfma_f32_16x16x32_bf16 v[78:81], v[130:133], v[226:229], 0
	v_mfma_f32_16x16x32_bf16 v[70:73], v[138:141], v[226:229], 0
	v_mfma_f32_16x16x32_bf16 v[126:129], v[134:137], v[206:209], v[126:129]
	v_mfma_f32_16x16x32_bf16 v[118:121], v[142:145], v[206:209], v[118:121]
	v_mfma_f32_16x16x32_bf16 v[110:113], v[134:137], v[214:217], v[110:113]
	v_mfma_f32_16x16x32_bf16 v[102:105], v[142:145], v[214:217], v[102:105]
	v_mfma_f32_16x16x32_bf16 v[94:97], v[134:137], v[222:225], v[94:97]
	v_mfma_f32_16x16x32_bf16 v[86:89], v[142:145], v[222:225], v[86:89]
	v_mfma_f32_16x16x32_bf16 v[78:81], v[134:137], v[236:239], v[78:81]
	v_mfma_f32_16x16x32_bf16 v[70:73], v[142:145], v[236:239], v[70:73]
	s_setprio 0
	s_setprio 1
	v_mfma_f32_16x16x32_bf16 v[122:125], v[146:149], v[172:175], 0
	v_mfma_f32_16x16x32_bf16 v[114:117], v[164:167], v[172:175], 0
	v_mfma_f32_16x16x32_bf16 v[106:109], v[146:149], v[210:213], 0
	v_mfma_f32_16x16x32_bf16 v[98:101], v[164:167], v[210:213], 0
	v_mfma_f32_16x16x32_bf16 v[90:93], v[146:149], v[218:221], 0
	v_mfma_f32_16x16x32_bf16 v[82:85], v[164:167], v[218:221], 0
	v_mfma_f32_16x16x32_bf16 v[74:77], v[146:149], v[226:229], 0
	v_mfma_f32_16x16x32_bf16 v[66:69], v[164:167], v[226:229], 0
	v_mfma_f32_16x16x32_bf16 v[122:125], v[160:163], v[206:209], v[122:125]
	v_mfma_f32_16x16x32_bf16 v[114:117], v[168:171], v[206:209], v[114:117]
	v_mfma_f32_16x16x32_bf16 v[106:109], v[160:163], v[214:217], v[106:109]
	v_mfma_f32_16x16x32_bf16 v[98:101], v[168:171], v[214:217], v[98:101]
	v_mfma_f32_16x16x32_bf16 v[90:93], v[160:163], v[222:225], v[90:93]
	v_mfma_f32_16x16x32_bf16 v[82:85], v[168:171], v[222:225], v[82:85]
	v_mfma_f32_16x16x32_bf16 v[74:77], v[160:163], v[236:239], v[74:77]
	v_mfma_f32_16x16x32_bf16 v[66:69], v[168:171], v[236:239], v[66:69]
	s_setprio 0
	s_barrier
	s_add_i32 s29, s29, s44
	v_lshl_add_u64 v[176:177], s[30:31], 0, v[152:153]
	s_mov_b32 m0, s29
	ds_read_b128 v[172:175], v205 offset:16384
	ds_read_b128 v[206:209], v205 offset:17408
	ds_read_b128 v[210:213], v205 offset:18432
	ds_read_b128 v[214:217], v205 offset:19456
	ds_read_b128 v[218:221], v205 offset:20480
	ds_read_b128 v[222:225], v205 offset:21504
	ds_read_b128 v[226:229], v205 offset:22528
	ds_read_b128 v[236:239], v205 offset:23552
	global_load_lds_dwordx4 v[176:177], off
	s_add_i32 m0, s29, 0x2000
	v_lshl_add_u64 v[230:231], s[30:31], 0, v[154:155]
	s_add_u32 s30, s30, s12
	s_addc_u32 s31, s31, s13
	s_add_i32 s21, s21, s44
	global_load_lds_dwordx4 v[230:231], off
	v_lshl_add_u64 v[240:241], s[30:31], 0, v[152:153]
	s_mov_b32 m0, s21
	v_lshl_add_u64 v[242:243], s[30:31], 0, v[154:155]
	global_load_lds_dwordx4 v[240:241], off
	s_add_i32 m0, s21, 0x2000
	v_lshl_add_u64 v[244:245], s[4:5], 0, v[152:153]
	global_load_lds_dwordx4 v[242:243], off
	s_mov_b32 m0, s27
	v_lshl_add_u64 v[246:247], s[4:5], 0, v[154:155]
	global_load_lds_dwordx4 v[244:245], off
	s_mov_b32 m0, s45
	s_nop 0
	global_load_lds_dwordx4 v[246:247], off
	s_waitcnt vmcnt(8)
	s_waitcnt lgkmcnt(0)
	s_barrier
	s_setprio 1
	s_waitcnt lgkmcnt(0)
	v_mfma_f32_16x16x32_bf16 v[62:65], v[130:133], v[172:175], 0
	v_mfma_f32_16x16x32_bf16 v[54:57], v[138:141], v[172:175], 0
	v_mfma_f32_16x16x32_bf16 v[46:49], v[130:133], v[210:213], 0
	v_mfma_f32_16x16x32_bf16 v[38:41], v[138:141], v[210:213], 0
	v_mfma_f32_16x16x32_bf16 v[30:33], v[130:133], v[218:221], 0
	v_mfma_f32_16x16x32_bf16 v[22:25], v[138:141], v[218:221], 0
	v_mfma_f32_16x16x32_bf16 v[14:17], v[130:133], v[226:229], 0
	v_mfma_f32_16x16x32_bf16 v[6:9], v[138:141], v[226:229], 0
	v_mfma_f32_16x16x32_bf16 v[62:65], v[134:137], v[206:209], v[62:65]
	v_mfma_f32_16x16x32_bf16 v[54:57], v[142:145], v[206:209], v[54:57]
	v_mfma_f32_16x16x32_bf16 v[46:49], v[134:137], v[214:217], v[46:49]
	v_mfma_f32_16x16x32_bf16 v[38:41], v[142:145], v[214:217], v[38:41]
	v_mfma_f32_16x16x32_bf16 v[30:33], v[134:137], v[222:225], v[30:33]
	v_mfma_f32_16x16x32_bf16 v[22:25], v[142:145], v[222:225], v[22:25]
	v_mfma_f32_16x16x32_bf16 v[14:17], v[134:137], v[236:239], v[14:17]
	v_mfma_f32_16x16x32_bf16 v[6:9], v[142:145], v[236:239], v[6:9]
	s_setprio 0
	s_setprio 1
	v_mfma_f32_16x16x32_bf16 v[58:61], v[146:149], v[172:175], 0
	v_mfma_f32_16x16x32_bf16 v[50:53], v[164:167], v[172:175], 0
	v_mfma_f32_16x16x32_bf16 v[42:45], v[146:149], v[210:213], 0
	v_mfma_f32_16x16x32_bf16 v[34:37], v[164:167], v[210:213], 0
	v_mfma_f32_16x16x32_bf16 v[26:29], v[146:149], v[218:221], 0
	v_mfma_f32_16x16x32_bf16 v[18:21], v[164:167], v[218:221], 0
	v_mfma_f32_16x16x32_bf16 v[10:13], v[146:149], v[226:229], 0
	v_mfma_f32_16x16x32_bf16 v[2:5], v[164:167], v[226:229], 0
	v_mfma_f32_16x16x32_bf16 v[58:61], v[160:163], v[206:209], v[58:61]
	v_mfma_f32_16x16x32_bf16 v[50:53], v[168:171], v[206:209], v[50:53]
	v_mfma_f32_16x16x32_bf16 v[42:45], v[160:163], v[214:217], v[42:45]
	v_mfma_f32_16x16x32_bf16 v[34:37], v[168:171], v[214:217], v[34:37]
	v_mfma_f32_16x16x32_bf16 v[26:29], v[160:163], v[222:225], v[26:29]
	v_mfma_f32_16x16x32_bf16 v[18:21], v[168:171], v[222:225], v[18:21]
	v_mfma_f32_16x16x32_bf16 v[10:13], v[160:163], v[236:239], v[10:13]
	v_mfma_f32_16x16x32_bf16 v[2:5], v[168:171], v[236:239], v[2:5]
	s_setprio 0
	s_barrier
	s_add_i32 s21, 0, 0x18000
	v_add_u32_e32 v0, s21, v204
	s_add_i32 s29, 0, 0x1c000
	ds_read_b128 v[130:133], v0
	ds_read_b128 v[134:137], v0 offset:1024
	ds_read_b128 v[138:141], v0 offset:2048
	ds_read_b128 v[142:145], v0 offset:3072
	v_add_u32_e32 v0, s29, v204
	ds_read_b128 v[146:149], v0
	ds_read_b128 v[160:163], v0 offset:1024
	ds_read_b128 v[164:167], v0 offset:2048
	ds_read_b128 v[168:171], v0 offset:3072
	s_add_u32 s4, s4, s12
	s_addc_u32 s5, s5, s13
	s_mov_b32 m0, s46
	v_lshl_add_u64 v[248:249], s[4:5], 0, v[152:153]
	ds_read_b128 v[172:175], v205 offset:32768
	ds_read_b128 v[206:209], v205 offset:33792
	ds_read_b128 v[210:213], v205 offset:34816
	ds_read_b128 v[214:217], v205 offset:35840
	ds_read_b128 v[218:221], v205 offset:36864
	ds_read_b128 v[222:225], v205 offset:37888
	ds_read_b128 v[226:229], v205 offset:38912
	ds_read_b128 v[236:239], v205 offset:39936
	global_load_lds_dwordx4 v[248:249], off
	v_lshl_add_u64 v[248:249], s[4:5], 0, v[154:155]
	s_mov_b32 m0, s47
	s_nop 0
	global_load_lds_dwordx4 v[248:249], off
	s_waitcnt vmcnt(8)
	s_waitcnt lgkmcnt(0)
	s_barrier
	s_setprio 1
	s_waitcnt lgkmcnt(0)
	v_mfma_f32_16x16x32_bf16 v[126:129], v[130:133], v[172:175], v[126:129]
	v_mfma_f32_16x16x32_bf16 v[118:121], v[138:141], v[172:175], v[118:121]
	v_mfma_f32_16x16x32_bf16 v[110:113], v[130:133], v[210:213], v[110:113]
	v_mfma_f32_16x16x32_bf16 v[102:105], v[138:141], v[210:213], v[102:105]
	v_mfma_f32_16x16x32_bf16 v[94:97], v[130:133], v[218:221], v[94:97]
	v_mfma_f32_16x16x32_bf16 v[86:89], v[138:141], v[218:221], v[86:89]
	v_mfma_f32_16x16x32_bf16 v[78:81], v[130:133], v[226:229], v[78:81]
	v_mfma_f32_16x16x32_bf16 v[70:73], v[138:141], v[226:229], v[70:73]
	v_mfma_f32_16x16x32_bf16 v[126:129], v[134:137], v[206:209], v[126:129]
	v_mfma_f32_16x16x32_bf16 v[118:121], v[142:145], v[206:209], v[118:121]
	v_mfma_f32_16x16x32_bf16 v[110:113], v[134:137], v[214:217], v[110:113]
	v_mfma_f32_16x16x32_bf16 v[102:105], v[142:145], v[214:217], v[102:105]
	v_mfma_f32_16x16x32_bf16 v[94:97], v[134:137], v[222:225], v[94:97]
	v_mfma_f32_16x16x32_bf16 v[86:89], v[142:145], v[222:225], v[86:89]
	v_mfma_f32_16x16x32_bf16 v[78:81], v[134:137], v[236:239], v[78:81]
	v_mfma_f32_16x16x32_bf16 v[70:73], v[142:145], v[236:239], v[70:73]
	s_setprio 0
	s_setprio 1
	v_mfma_f32_16x16x32_bf16 v[122:125], v[146:149], v[172:175], v[122:125]
	v_mfma_f32_16x16x32_bf16 v[114:117], v[164:167], v[172:175], v[114:117]
	v_mfma_f32_16x16x32_bf16 v[106:109], v[146:149], v[210:213], v[106:109]
	v_mfma_f32_16x16x32_bf16 v[98:101], v[164:167], v[210:213], v[98:101]
	v_mfma_f32_16x16x32_bf16 v[90:93], v[146:149], v[218:221], v[90:93]
	v_mfma_f32_16x16x32_bf16 v[82:85], v[164:167], v[218:221], v[82:85]
	v_mfma_f32_16x16x32_bf16 v[74:77], v[146:149], v[226:229], v[74:77]
	v_mfma_f32_16x16x32_bf16 v[66:69], v[164:167], v[226:229], v[66:69]
	v_mfma_f32_16x16x32_bf16 v[122:125], v[160:163], v[206:209], v[122:125]
	v_mfma_f32_16x16x32_bf16 v[114:117], v[168:171], v[206:209], v[114:117]
	v_mfma_f32_16x16x32_bf16 v[106:109], v[160:163], v[214:217], v[106:109]
	v_mfma_f32_16x16x32_bf16 v[98:101], v[168:171], v[214:217], v[98:101]
	v_mfma_f32_16x16x32_bf16 v[90:93], v[160:163], v[222:225], v[90:93]
	v_mfma_f32_16x16x32_bf16 v[82:85], v[168:171], v[222:225], v[82:85]
	v_mfma_f32_16x16x32_bf16 v[74:77], v[160:163], v[236:239], v[74:77]
	v_mfma_f32_16x16x32_bf16 v[66:69], v[168:171], v[236:239], v[66:69]
	s_setprio 0
	s_barrier
	s_add_i32 s4, s21, s44
	v_lshl_add_u64 v[176:177], v[176:177], 0, s[92:93]
	s_mov_b32 m0, s4
	ds_read_b128 v[172:175], v205 offset:49152
	ds_read_b128 v[206:209], v205 offset:50176
	ds_read_b128 v[210:213], v205 offset:51200
	ds_read_b128 v[214:217], v205 offset:52224
	ds_read_b128 v[218:221], v205 offset:53248
	ds_read_b128 v[222:225], v205 offset:54272
	ds_read_b128 v[226:229], v205 offset:55296
	ds_read_b128 v[236:239], v205 offset:56320
	global_load_lds_dwordx4 v[176:177], off
	v_lshl_add_u64 v[176:177], v[230:231], 0, s[92:93]
	s_add_i32 m0, s4, 0x2000
	s_add_i32 s4, s29, s44
	global_load_lds_dwordx4 v[176:177], off
	v_lshl_add_u64 v[176:177], v[240:241], 0, s[92:93]
	s_mov_b32 m0, s4
	s_nop 0
	global_load_lds_dwordx4 v[176:177], off
	v_lshl_add_u64 v[176:177], v[242:243], 0, s[92:93]
	s_add_i32 m0, s4, 0x2000
	s_nop 0
	global_load_lds_dwordx4 v[176:177], off
	v_lshl_add_u64 v[176:177], v[244:245], 0, s[92:93]
	s_mov_b32 m0, s48
	s_nop 0
	global_load_lds_dwordx4 v[176:177], off
	v_lshl_add_u64 v[176:177], v[246:247], 0, s[92:93]
	s_mov_b32 m0, s49
	s_nop 0
	global_load_lds_dwordx4 v[176:177], off
	s_waitcnt vmcnt(8)
	s_waitcnt lgkmcnt(0)
	s_barrier
	s_setprio 1
	s_waitcnt lgkmcnt(0)
	v_mfma_f32_16x16x32_bf16 v[62:65], v[130:133], v[172:175], v[62:65]
	v_mfma_f32_16x16x32_bf16 v[54:57], v[138:141], v[172:175], v[54:57]
	v_mfma_f32_16x16x32_bf16 v[46:49], v[130:133], v[210:213], v[46:49]
	v_mfma_f32_16x16x32_bf16 v[38:41], v[138:141], v[210:213], v[38:41]
	v_mfma_f32_16x16x32_bf16 v[30:33], v[130:133], v[218:221], v[30:33]
	v_mfma_f32_16x16x32_bf16 v[22:25], v[138:141], v[218:221], v[22:25]
	v_mfma_f32_16x16x32_bf16 v[14:17], v[130:133], v[226:229], v[14:17]
	v_mfma_f32_16x16x32_bf16 v[6:9], v[138:141], v[226:229], v[6:9]
	v_mfma_f32_16x16x32_bf16 v[62:65], v[134:137], v[206:209], v[62:65]
	v_mfma_f32_16x16x32_bf16 v[54:57], v[142:145], v[206:209], v[54:57]
	v_mfma_f32_16x16x32_bf16 v[46:49], v[134:137], v[214:217], v[46:49]
	v_mfma_f32_16x16x32_bf16 v[38:41], v[142:145], v[214:217], v[38:41]
	v_mfma_f32_16x16x32_bf16 v[30:33], v[134:137], v[222:225], v[30:33]
	v_mfma_f32_16x16x32_bf16 v[22:25], v[142:145], v[222:225], v[22:25]
	v_mfma_f32_16x16x32_bf16 v[14:17], v[134:137], v[236:239], v[14:17]
	v_mfma_f32_16x16x32_bf16 v[6:9], v[142:145], v[236:239], v[6:9]
	s_setprio 0
	s_setprio 1
	v_mfma_f32_16x16x32_bf16 v[58:61], v[146:149], v[172:175], v[58:61]
	v_mfma_f32_16x16x32_bf16 v[50:53], v[164:167], v[172:175], v[50:53]
	v_mfma_f32_16x16x32_bf16 v[42:45], v[146:149], v[210:213], v[42:45]
	v_mfma_f32_16x16x32_bf16 v[34:37], v[164:167], v[210:213], v[34:37]
	v_mfma_f32_16x16x32_bf16 v[26:29], v[146:149], v[218:221], v[26:29]
	v_mfma_f32_16x16x32_bf16 v[18:21], v[164:167], v[218:221], v[18:21]
	v_mfma_f32_16x16x32_bf16 v[10:13], v[146:149], v[226:229], v[10:13]
	v_mfma_f32_16x16x32_bf16 v[2:5], v[164:167], v[226:229], v[2:5]
	v_mfma_f32_16x16x32_bf16 v[58:61], v[160:163], v[206:209], v[58:61]
	v_mfma_f32_16x16x32_bf16 v[50:53], v[168:171], v[206:209], v[50:53]
	v_mfma_f32_16x16x32_bf16 v[42:45], v[160:163], v[214:217], v[42:45]
	v_mfma_f32_16x16x32_bf16 v[34:37], v[168:171], v[214:217], v[34:37]
	v_mfma_f32_16x16x32_bf16 v[26:29], v[160:163], v[222:225], v[26:29]
	v_mfma_f32_16x16x32_bf16 v[18:21], v[168:171], v[222:225], v[18:21]
	v_mfma_f32_16x16x32_bf16 v[10:13], v[160:163], v[236:239], v[10:13]
	v_mfma_f32_16x16x32_bf16 v[2:5], v[168:171], v[236:239], v[2:5]
	s_setprio 0
	s_barrier
	s_add_u32 s7, s7, 0x100
	s_addc_u32 s8, s8, 0
	s_add_u32 s2, s2, 0x100
	s_addc_u32 s3, s3, 0
	s_cmp_ge_i32 s9, s28
	s_mov_b32 s4, s9
	s_cbranch_scc0 .LBB0_811
	s_branch .Lk_exit

.Lk_exit:
	s_and_b64 vcc, exec, s[18:19]
	s_cbranch_vccz .LBB0_814

.LBB0_828:
	s_andn2_b64 vcc, exec, s[2:3]
	s_cbranch_vccnz .LBB0_830
	s_branch .Lrettv_fast
	v_readlane_b32 s2, v253, 36
	v_ashrrev_i32_e32 v161, 31, v160
	v_lshlrev_b64 v[134:135], 8, v[160:161]
	v_mov_b32_e32 v0, s2
	ds_read_b64 v[132:133], v0
	s_mov_b32 s2, 0xfffc0000
	v_ashrrev_i32_e32 v136, 7, v162
	v_add_u32_e32 v0, 0x80, v162
	s_mov_b32 s3, -1
	s_waitcnt lgkmcnt(0)
	v_lshl_add_u64 v[132:133], v[132:133], 0, v[134:135]
	v_ashrrev_i32_e32 v137, 31, v136
	v_ashrrev_i32_e32 v130, 7, v0
	v_and_b32_e32 v0, 0x7c, v146
	v_lshl_add_u64 v[134:135], v[132:133], 0, s[2:3]
	v_lshlrev_b64 v[136:137], 19, v[136:137]
	v_lshl_add_u64 v[138:139], v[134:135], 0, v[136:137]
	v_lshlrev_b32_e32 v0, 1, v0
	v_lshl_add_u64 v[138:139], v[138:139], 0, v[0:1]
	v_cvt_pk_bf16_f32 v140, v126, v127
	v_cvt_pk_bf16_f32 v141, v128, v129
	global_store_dwordx2 v[138:139], v[140:141], off
	v_add_u32_e32 v140, 16, v162
	v_ashrrev_i32_e32 v138, 7, v140
	v_ashrrev_i32_e32 v139, 31, v138
	v_and_b32_e32 v142, 0x7c, v140
	v_lshlrev_b64 v[138:139], 19, v[138:139]
	v_ashrrev_i32_e32 v131, 31, v130
	v_lshl_add_u64 v[140:141], v[134:135], 0, v[138:139]
	v_lshlrev_b32_e32 v142, 1, v142
	v_mov_b32_e32 v143, v1
	v_lshlrev_b64 v[130:131], 19, v[130:131]
	v_lshl_add_u64 v[140:141], v[140:141], 0, v[142:143]
	v_cvt_pk_bf16_f32 v144, v118, v119
	v_cvt_pk_bf16_f32 v145, v120, v121
	global_store_dwordx2 v[140:141], v[144:145], off
	v_lshl_add_u64 v[140:141], v[134:135], 0, v[130:131]
	v_lshl_add_u64 v[140:141], v[140:141], 0, v[0:1]
	v_cvt_pk_bf16_f32 v144, v122, v123
	v_cvt_pk_bf16_f32 v145, v124, v125
	global_store_dwordx2 v[140:141], v[144:145], off
	v_add_u32_e32 v144, 0x90, v162
	v_ashrrev_i32_e32 v140, 7, v144
	v_ashrrev_i32_e32 v141, 31, v140
	v_and_b32_e32 v144, 0x7c, v144
	v_lshlrev_b64 v[140:141], 19, v[140:141]
	v_lshl_add_u64 v[134:135], v[134:135], 0, v[140:141]
	v_lshlrev_b32_e32 v144, 1, v144
	v_mov_b32_e32 v145, v1
	s_mov_b32 s2, 0xfffc1000
	v_lshl_add_u64 v[134:135], v[134:135], 0, v[144:145]
	v_cvt_pk_bf16_f32 v164, v114, v115
	v_cvt_pk_bf16_f32 v165, v116, v117
	s_mov_b32 s3, -1
	global_store_dwordx2 v[134:135], v[164:165], off
	v_lshl_add_u64 v[134:135], v[132:133], 0, s[2:3]
	v_lshl_add_u64 v[164:165], v[134:135], 0, v[136:137]
	v_lshl_add_u64 v[164:165], v[164:165], 0, v[0:1]
	v_cvt_pk_bf16_f32 v166, v110, v111
	v_cvt_pk_bf16_f32 v167, v112, v113
	global_store_dwordx2 v[164:165], v[166:167], off
	v_lshl_add_u64 v[164:165], v[134:135], 0, v[138:139]
	v_lshl_add_u64 v[164:165], v[164:165], 0, v[142:143]
	v_cvt_pk_bf16_f32 v166, v102, v103
	v_cvt_pk_bf16_f32 v167, v104, v105
	global_store_dwordx2 v[164:165], v[166:167], off
	v_lshl_add_u64 v[164:165], v[134:135], 0, v[130:131]
	v_lshl_add_u64 v[164:165], v[164:165], 0, v[0:1]
	v_cvt_pk_bf16_f32 v166, v106, v107
	v_cvt_pk_bf16_f32 v167, v108, v109
	v_lshl_add_u64 v[134:135], v[134:135], 0, v[140:141]
	s_mov_b32 s2, 0xfffc2000
	global_store_dwordx2 v[164:165], v[166:167], off
	v_lshl_add_u64 v[134:135], v[134:135], 0, v[144:145]
	v_cvt_pk_bf16_f32 v164, v98, v99
	v_cvt_pk_bf16_f32 v165, v100, v101
	s_mov_b32 s3, -1
	global_store_dwordx2 v[134:135], v[164:165], off
	v_lshl_add_u64 v[134:135], v[132:133], 0, s[2:3]
	v_lshl_add_u64 v[164:165], v[134:135], 0, v[136:137]
	v_lshl_add_u64 v[164:165], v[164:165], 0, v[0:1]
	v_cvt_pk_bf16_f32 v166, v94, v95
	v_cvt_pk_bf16_f32 v167, v96, v97
	global_store_dwordx2 v[164:165], v[166:167], off
	v_lshl_add_u64 v[164:165], v[134:135], 0, v[138:139]
	v_lshl_add_u64 v[164:165], v[164:165], 0, v[142:143]
	v_cvt_pk_bf16_f32 v166, v86, v87
	v_cvt_pk_bf16_f32 v167, v88, v89
	global_store_dwordx2 v[164:165], v[166:167], off
	v_lshl_add_u64 v[164:165], v[134:135], 0, v[130:131]
	v_lshl_add_u64 v[164:165], v[164:165], 0, v[0:1]
	v_cvt_pk_bf16_f32 v166, v90, v91
	v_cvt_pk_bf16_f32 v167, v92, v93
	v_lshl_add_u64 v[134:135], v[134:135], 0, v[140:141]
	s_mov_b32 s2, 0xfffc3000
	global_store_dwordx2 v[164:165], v[166:167], off
	v_lshl_add_u64 v[134:135], v[134:135], 0, v[144:145]
	v_cvt_pk_bf16_f32 v164, v82, v83
	v_cvt_pk_bf16_f32 v165, v84, v85
	s_mov_b32 s3, -1
	global_store_dwordx2 v[134:135], v[164:165], off
	v_lshl_add_u64 v[134:135], v[132:133], 0, s[2:3]
	v_lshl_add_u64 v[164:165], v[134:135], 0, v[136:137]
	v_lshl_add_u64 v[164:165], v[164:165], 0, v[0:1]
	v_cvt_pk_bf16_f32 v166, v78, v79
	v_cvt_pk_bf16_f32 v167, v80, v81
	global_store_dwordx2 v[164:165], v[166:167], off
	v_lshl_add_u64 v[164:165], v[134:135], 0, v[138:139]
	v_lshl_add_u64 v[164:165], v[164:165], 0, v[142:143]
	v_cvt_pk_bf16_f32 v166, v70, v71
	v_cvt_pk_bf16_f32 v167, v72, v73
	global_store_dwordx2 v[164:165], v[166:167], off
	v_lshl_add_u64 v[164:165], v[134:135], 0, v[130:131]
	v_lshl_add_u64 v[164:165], v[164:165], 0, v[0:1]
	v_cvt_pk_bf16_f32 v166, v74, v75
	v_cvt_pk_bf16_f32 v167, v76, v77
	v_lshl_add_u64 v[134:135], v[134:135], 0, v[140:141]
	s_mov_b32 s2, 0xfffc8000
	global_store_dwordx2 v[164:165], v[166:167], off
	v_lshl_add_u64 v[134:135], v[134:135], 0, v[144:145]
	v_cvt_pk_bf16_f32 v164, v66, v67
	v_cvt_pk_bf16_f32 v165, v68, v69
	s_mov_b32 s3, -1
	global_store_dwordx2 v[134:135], v[164:165], off
	v_lshl_add_u64 v[134:135], v[132:133], 0, s[2:3]
	v_lshl_add_u64 v[164:165], v[134:135], 0, v[136:137]
	v_lshl_add_u64 v[164:165], v[164:165], 0, v[0:1]
	v_cvt_pk_bf16_f32 v166, v62, v63
	v_cvt_pk_bf16_f32 v167, v64, v65
	global_store_dwordx2 v[164:165], v[166:167], off
	v_lshl_add_u64 v[164:165], v[134:135], 0, v[138:139]
	v_lshl_add_u64 v[164:165], v[164:165], 0, v[142:143]
	v_cvt_pk_bf16_f32 v166, v54, v55
	v_cvt_pk_bf16_f32 v167, v56, v57
	global_store_dwordx2 v[164:165], v[166:167], off
	v_lshl_add_u64 v[164:165], v[134:135], 0, v[130:131]
	v_lshl_add_u64 v[164:165], v[164:165], 0, v[0:1]
	v_cvt_pk_bf16_f32 v166, v58, v59
	v_cvt_pk_bf16_f32 v167, v60, v61
	v_lshl_add_u64 v[134:135], v[134:135], 0, v[140:141]
	s_mov_b32 s2, 0xfffc9000
	global_store_dwordx2 v[164:165], v[166:167], off
	v_lshl_add_u64 v[134:135], v[134:135], 0, v[144:145]
	v_cvt_pk_bf16_f32 v164, v50, v51
	v_cvt_pk_bf16_f32 v165, v52, v53
	s_mov_b32 s3, -1
	global_store_dwordx2 v[134:135], v[164:165], off
	v_lshl_add_u64 v[134:135], v[132:133], 0, s[2:3]
	v_lshl_add_u64 v[164:165], v[134:135], 0, v[136:137]
	v_lshl_add_u64 v[164:165], v[164:165], 0, v[0:1]
	v_cvt_pk_bf16_f32 v166, v46, v47
	v_cvt_pk_bf16_f32 v167, v48, v49
	global_store_dwordx2 v[164:165], v[166:167], off
	v_lshl_add_u64 v[164:165], v[134:135], 0, v[138:139]
	v_lshl_add_u64 v[164:165], v[164:165], 0, v[142:143]
	v_cvt_pk_bf16_f32 v166, v38, v39
	v_cvt_pk_bf16_f32 v167, v40, v41
	global_store_dwordx2 v[164:165], v[166:167], off
	v_lshl_add_u64 v[164:165], v[134:135], 0, v[130:131]
	v_lshl_add_u64 v[164:165], v[164:165], 0, v[0:1]
	v_cvt_pk_bf16_f32 v166, v42, v43
	v_cvt_pk_bf16_f32 v167, v44, v45
	v_lshl_add_u64 v[134:135], v[134:135], 0, v[140:141]
	s_mov_b32 s2, 0xfffca000
	global_store_dwordx2 v[164:165], v[166:167], off
	v_lshl_add_u64 v[134:135], v[134:135], 0, v[144:145]
	v_cvt_pk_bf16_f32 v164, v34, v35
	v_cvt_pk_bf16_f32 v165, v36, v37
	s_mov_b32 s3, -1
	global_store_dwordx2 v[134:135], v[164:165], off
	v_lshl_add_u64 v[134:135], v[132:133], 0, s[2:3]
	v_lshl_add_u64 v[164:165], v[134:135], 0, v[136:137]
	v_lshl_add_u64 v[164:165], v[164:165], 0, v[0:1]
	v_cvt_pk_bf16_f32 v166, v30, v31
	v_cvt_pk_bf16_f32 v167, v32, v33
	global_store_dwordx2 v[164:165], v[166:167], off
	v_lshl_add_u64 v[164:165], v[134:135], 0, v[138:139]
	v_lshl_add_u64 v[164:165], v[164:165], 0, v[142:143]
	v_cvt_pk_bf16_f32 v166, v22, v23
	v_cvt_pk_bf16_f32 v167, v24, v25
	global_store_dwordx2 v[164:165], v[166:167], off
	v_lshl_add_u64 v[164:165], v[134:135], 0, v[130:131]
	s_mov_b32 s2, 0xfffcb000
	v_lshl_add_u64 v[164:165], v[164:165], 0, v[0:1]
	v_cvt_pk_bf16_f32 v166, v26, v27
	v_cvt_pk_bf16_f32 v167, v28, v29
	v_lshl_add_u64 v[134:135], v[134:135], 0, v[140:141]
	s_mov_b32 s3, -1
	global_store_dwordx2 v[164:165], v[166:167], off
	v_lshl_add_u64 v[134:135], v[134:135], 0, v[144:145]
	v_cvt_pk_bf16_f32 v164, v18, v19
	v_cvt_pk_bf16_f32 v165, v20, v21
	v_lshl_add_u64 v[132:133], v[132:133], 0, s[2:3]
	global_store_dwordx2 v[134:135], v[164:165], off
	v_lshl_add_u64 v[134:135], v[132:133], 0, v[136:137]
	v_lshl_add_u64 v[134:135], v[134:135], 0, v[0:1]
	v_cvt_pk_bf16_f32 v136, v14, v15
	v_cvt_pk_bf16_f32 v137, v16, v17
	global_store_dwordx2 v[134:135], v[136:137], off
	v_lshl_add_u64 v[134:135], v[132:133], 0, v[138:139]
	v_lshl_add_u64 v[134:135], v[134:135], 0, v[142:143]
	v_cvt_pk_bf16_f32 v136, v6, v7
	v_cvt_pk_bf16_f32 v137, v8, v9
	v_lshl_add_u64 v[130:131], v[132:133], 0, v[130:131]
	global_store_dwordx2 v[134:135], v[136:137], off
	v_lshl_add_u64 v[130:131], v[130:131], 0, v[0:1]
	v_cvt_pk_bf16_f32 v134, v10, v11
	v_cvt_pk_bf16_f32 v135, v12, v13
	global_store_dwordx2 v[130:131], v[134:135], off
	v_lshl_add_u64 v[130:131], v[132:133], 0, v[140:141]
	v_lshl_add_u64 v[130:131], v[130:131], 0, v[144:145]
	v_cvt_pk_bf16_f32 v132, v2, v3
	v_cvt_pk_bf16_f32 v133, v4, v5
	global_store_dwordx2 v[130:131], v[132:133], off

.Lrettv_fast:
	v_readlane_b32 s4, v253, 36
	v_mov_b32_e32 v170, s4
	ds_read_b64 v[174:175], v170
	v_ashrrev_i32_e32 v161, 31, v160
	v_lshlrev_b64 v[172:173], 8, v[160:161]
	v_ashrrev_i32_e32 v168, 7, v162
	v_ashrrev_i32_e32 v169, 31, v168
	v_lshlrev_b64 v[168:169], 19, v[168:169]
	v_and_b32_e32 v170, 0x7c, v146
	v_lshlrev_b32_e32 v171, 2, v203
	v_sub_u32_e32 v170, v170, v171
	v_and_b32_e32 v171, 1, v203
	v_lshl_add_u32 v170, v171, 4, v170
	v_lshrrev_b32_e32 v171, 1, v203
	v_lshl_add_u32 v170, v171, 3, v170
	v_lshlrev_b32_e32 v170, 1, v170
	v_mov_b32_e32 v171, 0
	s_mov_b32 s4, 0xfffc0000
	s_mov_b32 s5, -1
	s_waitcnt lgkmcnt(0)
	v_lshl_add_u64 v[172:173], v[172:173], 0, v[174:175]
	v_lshl_add_u64 v[172:173], v[172:173], 0, s[4:5]
	v_lshl_add_u64 v[172:173], v[172:173], 0, v[168:169]
	v_lshl_add_u64 v[172:173], v[172:173], 0, v[170:171]
	s_mov_b64 s[4:5], 0x80000
	v_lshl_add_u64 v[174:175], v[172:173], 0, s[4:5]
	s_mov_b64 s[6:7], 0x1000
	s_mov_b64 s[8:9], 0x5000
	v_cvt_pk_bf16_f32 v206, v126, v127
	v_cvt_pk_bf16_f32 v207, v128, v129
	v_cvt_pk_bf16_f32 v208, v118, v119
	v_cvt_pk_bf16_f32 v209, v120, v121
	v_cvt_pk_bf16_f32 v210, v122, v123
	v_cvt_pk_bf16_f32 v211, v124, v125
	v_cvt_pk_bf16_f32 v212, v114, v115
	v_cvt_pk_bf16_f32 v213, v116, v117
	v_permlane16_swap_b32_e32 v206, v208
	v_permlane16_swap_b32_e32 v207, v209
	global_store_dwordx4 v[172:173], v[206:209], off
	s_nop 1
	v_permlane16_swap_b32_e32 v210, v212
	v_permlane16_swap_b32_e32 v211, v213
	global_store_dwordx4 v[174:175], v[210:213], off
	s_nop 0
	v_lshl_add_u64 v[172:173], v[172:173], 0, s[6:7]
	v_lshl_add_u64 v[174:175], v[174:175], 0, s[6:7]
	v_cvt_pk_bf16_f32 v214, v110, v111
	v_cvt_pk_bf16_f32 v215, v112, v113
	v_cvt_pk_bf16_f32 v216, v102, v103
	v_cvt_pk_bf16_f32 v217, v104, v105
	v_cvt_pk_bf16_f32 v218, v106, v107
	v_cvt_pk_bf16_f32 v219, v108, v109
	v_cvt_pk_bf16_f32 v220, v98, v99
	v_cvt_pk_bf16_f32 v221, v100, v101
	v_permlane16_swap_b32_e32 v214, v216
	v_permlane16_swap_b32_e32 v215, v217
	global_store_dwordx4 v[172:173], v[214:217], off
	s_nop 1
	v_permlane16_swap_b32_e32 v218, v220
	v_permlane16_swap_b32_e32 v219, v221
	global_store_dwordx4 v[174:175], v[218:221], off
	s_nop 0
	v_lshl_add_u64 v[172:173], v[172:173], 0, s[6:7]
	v_lshl_add_u64 v[174:175], v[174:175], 0, s[6:7]
	v_cvt_pk_bf16_f32 v222, v94, v95
	v_cvt_pk_bf16_f32 v223, v96, v97
	v_cvt_pk_bf16_f32 v224, v86, v87
	v_cvt_pk_bf16_f32 v225, v88, v89
	v_cvt_pk_bf16_f32 v226, v90, v91
	v_cvt_pk_bf16_f32 v227, v92, v93
	v_cvt_pk_bf16_f32 v228, v82, v83
	v_cvt_pk_bf16_f32 v229, v84, v85
	v_permlane16_swap_b32_e32 v222, v224
	v_permlane16_swap_b32_e32 v223, v225
	global_store_dwordx4 v[172:173], v[222:225], off
	s_nop 1
	v_permlane16_swap_b32_e32 v226, v228
	v_permlane16_swap_b32_e32 v227, v229
	global_store_dwordx4 v[174:175], v[226:229], off
	s_nop 0
	v_lshl_add_u64 v[172:173], v[172:173], 0, s[6:7]
	v_lshl_add_u64 v[174:175], v[174:175], 0, s[6:7]
	v_cvt_pk_bf16_f32 v236, v78, v79
	v_cvt_pk_bf16_f32 v237, v80, v81
	v_cvt_pk_bf16_f32 v238, v70, v71
	v_cvt_pk_bf16_f32 v239, v72, v73
	v_cvt_pk_bf16_f32 v240, v74, v75
	v_cvt_pk_bf16_f32 v241, v76, v77
	v_cvt_pk_bf16_f32 v242, v66, v67
	v_cvt_pk_bf16_f32 v243, v68, v69
	v_permlane16_swap_b32_e32 v236, v238
	v_permlane16_swap_b32_e32 v237, v239
	global_store_dwordx4 v[172:173], v[236:239], off
	s_nop 1
	v_permlane16_swap_b32_e32 v240, v242
	v_permlane16_swap_b32_e32 v241, v243
	global_store_dwordx4 v[174:175], v[240:243], off
	s_nop 0
	v_lshl_add_u64 v[172:173], v[172:173], 0, s[8:9]
	v_lshl_add_u64 v[174:175], v[174:175], 0, s[8:9]
	v_cvt_pk_bf16_f32 v244, v62, v63
	v_cvt_pk_bf16_f32 v245, v64, v65
	v_cvt_pk_bf16_f32 v246, v54, v55
	v_cvt_pk_bf16_f32 v247, v56, v57
	v_cvt_pk_bf16_f32 v206, v58, v59
	v_cvt_pk_bf16_f32 v207, v60, v61
	v_cvt_pk_bf16_f32 v208, v50, v51
	v_cvt_pk_bf16_f32 v209, v52, v53
	v_permlane16_swap_b32_e32 v244, v246
	v_permlane16_swap_b32_e32 v245, v247
	global_store_dwordx4 v[172:173], v[244:247], off
	s_nop 1
	v_permlane16_swap_b32_e32 v206, v208
	v_permlane16_swap_b32_e32 v207, v209
	global_store_dwordx4 v[174:175], v[206:209], off
	s_nop 0
	v_lshl_add_u64 v[172:173], v[172:173], 0, s[6:7]
	v_lshl_add_u64 v[174:175], v[174:175], 0, s[6:7]
	v_cvt_pk_bf16_f32 v210, v46, v47
	v_cvt_pk_bf16_f32 v211, v48, v49
	v_cvt_pk_bf16_f32 v212, v38, v39
	v_cvt_pk_bf16_f32 v213, v40, v41
	v_cvt_pk_bf16_f32 v214, v42, v43
	v_cvt_pk_bf16_f32 v215, v44, v45
	v_cvt_pk_bf16_f32 v216, v34, v35
	v_cvt_pk_bf16_f32 v217, v36, v37
	v_permlane16_swap_b32_e32 v210, v212
	v_permlane16_swap_b32_e32 v211, v213
	global_store_dwordx4 v[172:173], v[210:213], off
	s_nop 1
	v_permlane16_swap_b32_e32 v214, v216
	v_permlane16_swap_b32_e32 v215, v217
	global_store_dwordx4 v[174:175], v[214:217], off
	s_nop 0
	v_lshl_add_u64 v[172:173], v[172:173], 0, s[6:7]
	v_lshl_add_u64 v[174:175], v[174:175], 0, s[6:7]
	v_cvt_pk_bf16_f32 v218, v30, v31
	v_cvt_pk_bf16_f32 v219, v32, v33
	v_cvt_pk_bf16_f32 v220, v22, v23
	v_cvt_pk_bf16_f32 v221, v24, v25
	v_cvt_pk_bf16_f32 v222, v26, v27
	v_cvt_pk_bf16_f32 v223, v28, v29
	v_cvt_pk_bf16_f32 v224, v18, v19
	v_cvt_pk_bf16_f32 v225, v20, v21
	v_permlane16_swap_b32_e32 v218, v220
	v_permlane16_swap_b32_e32 v219, v221
	global_store_dwordx4 v[172:173], v[218:221], off
	s_nop 1
	v_permlane16_swap_b32_e32 v222, v224
	v_permlane16_swap_b32_e32 v223, v225
	global_store_dwordx4 v[174:175], v[222:225], off
	s_nop 0
	v_lshl_add_u64 v[172:173], v[172:173], 0, s[6:7]
	v_lshl_add_u64 v[174:175], v[174:175], 0, s[6:7]
	v_cvt_pk_bf16_f32 v226, v14, v15
	v_cvt_pk_bf16_f32 v227, v16, v17
	v_cvt_pk_bf16_f32 v228, v6, v7
	v_cvt_pk_bf16_f32 v229, v8, v9
	v_cvt_pk_bf16_f32 v236, v10, v11
	v_cvt_pk_bf16_f32 v237, v12, v13
	v_cvt_pk_bf16_f32 v238, v2, v3
	v_cvt_pk_bf16_f32 v239, v4, v5
	v_permlane16_swap_b32_e32 v226, v228
	v_permlane16_swap_b32_e32 v227, v229
	global_store_dwordx4 v[172:173], v[226:229], off
	s_nop 1
	v_permlane16_swap_b32_e32 v236, v238
	v_permlane16_swap_b32_e32 v237, v239
	global_store_dwordx4 v[174:175], v[236:239], off
	s_branch .LBB0_816
